# prompt attention tile body rewritten: batched LDS reads, reference max folded into QK accumulator init and raised lazily (exact online softmax, threshold 8), fewer VALU ops; plus v1 edits
# speedup vs baseline: 1.0179x; 1.0179x over previous
; #define AT_GLOAD(kt_) do { r0 = *(const u32x4v*)(KNb + (size_t)(kt_) * 64 * 512); \
;                 if (lo) { r1 = *(const u32x4v*)(KRb + (size_t)(kt_) * 64 * 32); r2 = *(const u32x4v*)(VTb + (kt_) * 64); } \
;                 else { r1 = *(const u32x4v*)(VTb + (kt_) * 64); } } while (0)
; #define AT_LSTORE(bf_) do { PG8_LAS unsigned char* bb_ = lds + (bf_) * BUF; *(PG8_LAS u32x4v*)(bb_ + k_st) = r0; \
;                 if (lo) { *(PG8_LAS u32x4v*)(bb_ + r_st) = r1; *(PG8_LAS u32x4v*)(bb_ + v_st) = r2; } else { *(PG8_LAS u32x4v*)(bb_ + v_st) = r1; } } while (0)
; __device__ void phase_attn(KP p, PG8_LAS unsigned char* lds, float* ldsf, int tid_in) {
;     ...
;             f32x4 o[4][2]; float mrun[2], lrun[2];
; #pragma unroll
;             for (int nb = 0; nb < 2; ++nb) { mrun[nb] = -1e30f; lrun[nb] = 0.f;
; #pragma unroll
;                 for (int df = 0; df < 4; ++df) o[df][nb] = (f32x4){0.f, 0.f, 0.f, 0.f}; }
;             u32x4v r0, r1, r2;
;     ...
;             AT_GLOAD(0); AT_LSTORE(0); __syncthreads();
.LBB0_516:
	s_or_b64 exec, exec, s[8:9]
	v_add_u32_e32 v4, 0, v166
	v_mov_b32_e32 v18, v9
	v_mov_b32_e32 v19, v9
	v_mov_b32_e32 v20, v9
	v_mov_b32_e32 v21, v9
	v_ashrrev_i32_e32 v171, 1, v14
	s_waitcnt vmcnt(0)
	ds_write_b128 v4, v[10:13] offset:13312
	v_mov_b32_e32 v8, v9
	v_mov_b64_e32 v[68:69], v[20:21]
	v_mov_b64_e32 v[14:15], v[18:19]
	v_mov_b64_e32 v[64:65], v[20:21]
	v_mov_b64_e32 v[10:11], v[18:19]
	v_mov_b64_e32 v[60:61], v[20:21]
	v_mov_b64_e32 v[4:5], v[18:19]
	v_mov_b64_e32 v[56:57], v[20:21]
	s_mov_b32 s12, 0
	v_mov_b32_e32 v132, 0xf149f2ca
	v_mov_b32_e32 v226, 0
	v_mov_b32_e32 v227, 0
	v_mov_b32_e32 v228, 0
	v_mov_b32_e32 v229, 0
	v_mov_b32_e32 v230, 0
	v_mov_b32_e32 v231, 0
	v_mov_b32_e32 v232, 0
	v_mov_b32_e32 v233, 0
	v_mov_b64_e32 v[128:129], v[120:121]
	v_mov_b64_e32 v[130:131], v[118:119]
	v_mov_b64_e32 v[66:67], v[18:19]
	v_mov_b64_e32 v[16:17], v[20:21]
	v_mov_b64_e32 v[62:63], v[18:19]
	v_mov_b64_e32 v[12:13], v[20:21]
	v_mov_b64_e32 v[58:59], v[18:19]
	v_mov_b64_e32 v[6:7], v[20:21]
	v_mov_b64_e32 v[54:55], v[18:19]
	v_mov_b32_e32 v74, 0xf149f2ca
	v_mov_b64_e32 v[124:125], v[8:9]
	s_waitcnt lgkmcnt(0)
	s_barrier

; #define PG8_LAS __attribute__((address_space(3)))
; __device__ void phase_attn(KP p, PG8_LAS unsigned char* lds, float* ldsf, int tid_in) {
;     ...
;             for (int kt = 0; kt < nt; ++kt) {
;                 if (kt + 1 < nt) AT_GLOAD(kt + 1);
;                 if (kt <= cw) {
;                     const PG8_LAS unsigned char* kb = lds + (kt & 1) * BUF;
;                     f32x4 st[4][2];
; #pragma unroll
;                     for (int f = 0; f < 4; ++f) {
;                         const bf16x8 a0 = *(const PG8_LAS bf16x8*)(kb + ka_rd + f * 16 * KS * 2);
;                         const bf16x8 a1 = *(const PG8_LAS bf16x8*)(kb + ka_rd + f * 16 * KS * 2 + 64);
;                         const bf16x8 a2 = *(const PG8_LAS bf16x8*)(kb + ka_rd + f * 16 * KS * 2 + 128);
; #pragma unroll
;                         for (int nb = 0; nb < 2; ++nb) {
;                             f32x4 c = {0.f, 0.f, 0.f, 0.f};
;                             c = __builtin_amdgcn_mfma_f32_16x16x32_bf16(a0, qf[0][nb], c, 0, 0, 0);
;                             c = __builtin_amdgcn_mfma_f32_16x16x32_bf16(a1, qf[1][nb], c, 0, 0, 0);
;                             c = __builtin_amdgcn_mfma_f32_16x16x32_bf16(a2, qf[2][nb], c, 0, 0, 0);
;                             st[f][nb] = c;
;                         }
;                     }
; #pragma unroll
;                     for (int nb = 0; nb < 2; ++nb) {
;                         float mx = -1e30f;
; #pragma unroll
;                         for (int f = 0; f < 4; ++f)
; #pragma unroll
;                             for (int r = 0; r < 4; ++r) mx = fmaxf(mx, st[f][nb][r]);
;                         mx = fmaxf(mx, shx(mx, 16, lane)); mx = fmaxf(mx, shx(mx, 32, lane));
;                         const float mn = fmaxf(mrun[nb], mx), al = __builtin_amdgcn_exp2f(mrun[nb] - mn); mrun[nb] = mn;
;                         float ps = 0.f;
; #pragma unroll
;                         for (int f = 0; f < 4; ++f)
; #pragma unroll
;                             for (int r = 0; r < 4; ++r) { const float e = __builtin_amdgcn_exp2f(st[f][nb][r] - mn); st[f][nb][r] = e; ps += e; }
;                         lrun[nb] = lrun[nb] * al + ps;
; #pragma unroll
;                         for (int df = 0; df < 4; ++df) o[df][nb] *= al;
;                     }
.LBB0_519:
	s_or_b64 exec, exec, s[8:9]
	global_load_dwordx4 v[50:53], v[50:51], off
	v_cmp_le_i32_e32 vcc, s12, v171
	s_and_saveexec_b64 s[8:9], vcc
	s_cbranch_execz .LBB0_521
	s_bitcmp1_b32 s12, 0
	s_cselect_b32 s12, 0x5800, 0
	s_add_i32 s12, s12, 0
	v_add_u32_e32 v8, s12, v167
	ds_read_b128 v[178:181], v8
	ds_read_b128 v[182:185], v8 offset:64
	ds_read_b128 v[186:189], v8 offset:128
	ds_read_b128 v[190:193], v8 offset:3328
	ds_read_b128 v[194:197], v8 offset:3392
	ds_read_b128 v[198:201], v8 offset:3456
	ds_read_b128 v[202:205], v8 offset:6656
	ds_read_b128 v[206:209], v8 offset:6720
	ds_read_b128 v[210:213], v8 offset:6784
	ds_read_b128 v[214:217], v8 offset:9984
	ds_read_b128 v[218:221], v8 offset:10048
	ds_read_b128 v[222:225], v8 offset:10112
	v_add_u32_e32 v92, s12, v170
	s_cmp_eq_u32 s40, 1
	s_cselect_b64 s[14:15], -1, 0
	s_waitcnt lgkmcnt(9)
	v_mfma_f32_16x16x32_bf16 v[134:137], v[178:181], v[22:25], v[226:229]
	v_mfma_f32_16x16x32_bf16 v[134:137], v[182:185], v[26:29], v[134:137]
	v_mfma_f32_16x16x32_bf16 v[134:137], v[186:189], v[38:41], v[134:137]
	s_waitcnt lgkmcnt(6)
	v_mfma_f32_16x16x32_bf16 v[138:141], v[190:193], v[22:25], v[226:229]
	v_mfma_f32_16x16x32_bf16 v[138:141], v[194:197], v[26:29], v[138:141]
	v_mfma_f32_16x16x32_bf16 v[138:141], v[198:201], v[38:41], v[138:141]
	s_waitcnt lgkmcnt(3)
	v_mfma_f32_16x16x32_bf16 v[142:145], v[202:205], v[22:25], v[226:229]
	v_mfma_f32_16x16x32_bf16 v[142:145], v[206:209], v[26:29], v[142:145]
	v_mfma_f32_16x16x32_bf16 v[142:145], v[210:213], v[38:41], v[142:145]
	s_waitcnt lgkmcnt(0)
	v_mfma_f32_16x16x32_bf16 v[146:149], v[214:217], v[22:25], v[226:229]
	v_mfma_f32_16x16x32_bf16 v[146:149], v[218:221], v[26:29], v[146:149]
	v_mfma_f32_16x16x32_bf16 v[146:149], v[222:225], v[38:41], v[146:149]
	v_mfma_f32_16x16x32_bf16 v[76:79], v[178:181], v[42:45], v[230:233]
	v_max3_f32 v156, v134, v135, v136
	v_max3_f32 v156, v156, v137, v138
	v_mfma_f32_16x16x32_bf16 v[76:79], v[182:185], v[30:33], v[76:79]
	v_max3_f32 v156, v156, v139, v140
	v_max3_f32 v156, v156, v141, v142
	v_mfma_f32_16x16x32_bf16 v[76:79], v[186:189], v[34:37], v[76:79]
	v_max3_f32 v156, v156, v143, v144
	v_max3_f32 v156, v156, v145, v146
	v_mfma_f32_16x16x32_bf16 v[80:83], v[190:193], v[42:45], v[230:233]
	v_max3_f32 v156, v156, v147, v148
	v_max_f32_e32 v156, v156, v149
	v_cmp_lt_f32_e32 vcc, 0x41000000, v156
	v_mfma_f32_16x16x32_bf16 v[80:83], v[194:197], v[30:33], v[80:83]
	v_mfma_f32_16x16x32_bf16 v[80:83], v[198:201], v[34:37], v[80:83]
	s_or_b64 vcc, vcc, s[14:15]
	s_cbranch_vccnz .Lat_resc0_1
.Lat_cont0_1:
	v_mfma_f32_16x16x32_bf16 v[84:87], v[202:205], v[42:45], v[230:233]
	v_exp_f32_e32 v134, v134
	v_exp_f32_e32 v135, v135
	v_mfma_f32_16x16x32_bf16 v[84:87], v[206:209], v[30:33], v[84:87]
	v_exp_f32_e32 v136, v136
	v_exp_f32_e32 v137, v137
	v_mfma_f32_16x16x32_bf16 v[84:87], v[210:213], v[34:37], v[84:87]
	v_exp_f32_e32 v138, v138
	v_exp_f32_e32 v139, v139
	v_mfma_f32_16x16x32_bf16 v[88:91], v[214:217], v[42:45], v[230:233]
	v_exp_f32_e32 v140, v140
	v_exp_f32_e32 v141, v141
	v_mfma_f32_16x16x32_bf16 v[88:91], v[218:221], v[30:33], v[88:91]
	v_exp_f32_e32 v142, v142
	v_exp_f32_e32 v143, v143
	v_mfma_f32_16x16x32_bf16 v[88:91], v[222:225], v[34:37], v[88:91]
	v_exp_f32_e32 v144, v144
	v_exp_f32_e32 v145, v145
	v_exp_f32_e32 v146, v146
	v_exp_f32_e32 v147, v147
	v_exp_f32_e32 v148, v148
	v_exp_f32_e32 v149, v149
	ds_read_b64 v[178:179], v92 offset:13312
	ds_read_b64 v[180:181], v92 offset:13344
	ds_read_b64 v[182:183], v92 offset:15616
	ds_read_b64 v[184:185], v92 offset:15648
	ds_read_b64 v[186:187], v92 offset:17920
	ds_read_b64 v[188:189], v92 offset:17952
	ds_read_b64 v[190:191], v92 offset:20224
	ds_read_b64 v[192:193], v92 offset:20256
	ds_read_b64 v[194:195], v92 offset:13376
	ds_read_b64 v[196:197], v92 offset:13408
	ds_read_b64 v[198:199], v92 offset:15680
	ds_read_b64 v[200:201], v92 offset:15712
	ds_read_b64 v[202:203], v92 offset:17984
	ds_read_b64 v[204:205], v92 offset:18016
	ds_read_b64 v[206:207], v92 offset:20288
	ds_read_b64 v[208:209], v92 offset:20320
	v_max3_f32 v157, v76, v77, v78
	v_max3_f32 v157, v157, v79, v80
	v_max3_f32 v157, v157, v81, v82
	v_max3_f32 v157, v157, v83, v84
	v_max3_f32 v157, v157, v85, v86
	v_max3_f32 v157, v157, v87, v88
	v_max3_f32 v157, v157, v89, v90
	v_max_f32_e32 v157, v157, v91
	v_cmp_lt_f32_e32 vcc, 0x41000000, v157
	v_add_f32_e32 v154, v134, v135
	v_add_f32_e32 v158, v136, v137
	s_or_b64 vcc, vcc, s[14:15]
	s_cbranch_vccnz .Lat_resc1_1
; #define PG8_LAS __attribute__((address_space(3)))
; __device__ __forceinline__ unsigned cvt_pk_bf16(float lo, float hi) { const f32x2c v = {lo, hi}; const bf16x2c b = __builtin_convertvector(v, bf16x2c); return __builtin_bit_cast(unsigned, b); }
; __device__ void phase_attn(KP p, PG8_LAS unsigned char* lds, float* ldsf, int tid_in) {
;     ...
;                         const float mn = fmaxf(mrun[nb], mx), al = __builtin_amdgcn_exp2f(mrun[nb] - mn); mrun[nb] = mn;
;                         float ps = 0.f;
; #pragma unroll
;                         for (int f = 0; f < 4; ++f)
; #pragma unroll
;                             for (int r = 0; r < 4; ++r) { const float e = __builtin_amdgcn_exp2f(st[f][nb][r] - mn); st[f][nb][r] = e; ps += e; }
;                         lrun[nb] = lrun[nb] * al + ps;
; #pragma unroll
;                         for (int df = 0; df < 4; ++df) o[df][nb] *= al;
;                     }
; #pragma unroll
;                     for (int kk = 0; kk < 2; ++kk) {
;                         bf16x8 pb[2];
; #pragma unroll
;                         for (int nb = 0; nb < 2; ++nb) {
;                             u32x4v t; t[0] = cvt_pk_bf16(st[2 * kk][nb][0], st[2 * kk][nb][1]); t[1] = cvt_pk_bf16(st[2 * kk][nb][2], st[2 * kk][nb][3]);
;                             t[2] = cvt_pk_bf16(st[2 * kk + 1][nb][0], st[2 * kk + 1][nb][1]); t[3] = cvt_pk_bf16(st[2 * kk + 1][nb][2], st[2 * kk + 1][nb][3]);
;                             pb[nb] = __builtin_bit_cast(bf16x8, t);
;                         }
; #pragma unroll
;                         for (int df = 0; df < 4; ++df) {
;                             const u32x2 v0 = *(const PG8_LAS u32x2*)(kb + va_rd + df * 16 * VS * 2 + kk * 64), v1 = *(const PG8_LAS u32x2*)(kb + va_rd + df * 16 * VS * 2 + kk * 64 + 32);
;                             u32x4v t; t[0] = v0[0]; t[1] = v0[1]; t[2] = v1[0]; t[3] = v1[1];
;                             const bf16x8 a = __builtin_bit_cast(bf16x8, t);
; #pragma unroll
;                             for (int nb = 0; nb < 2; ++nb) o[df][nb] = __builtin_amdgcn_mfma_f32_16x16x32_bf16(a, pb[nb], o[df][nb], 0, 0, 0);
;                         }
;                     }
;                 }
;                 if (kt + 1 < nt) AT_LSTORE((kt + 1) & 1);
;                 __syncthreads();
.Lat_cont1_1:
	v_add_f32_e32 v154, v154, v138
	v_add_f32_e32 v158, v158, v139
	v_add_f32_e32 v154, v154, v140
	v_add_f32_e32 v158, v158, v141
	v_add_f32_e32 v154, v154, v142
	v_add_f32_e32 v158, v158, v143
	v_add_f32_e32 v154, v154, v144
	v_add_f32_e32 v158, v158, v145
	v_add_f32_e32 v154, v154, v146
	v_add_f32_e32 v158, v158, v147
	v_add_f32_e32 v154, v154, v148
	v_add_f32_e32 v158, v158, v149
	v_add_f32_e32 v154, v154, v158
	v_add_f32_e32 v125, v125, v154
	v_cvt_pk_bf16_f32 v134, v134, v135
	v_cvt_pk_bf16_f32 v135, v136, v137
	v_cvt_pk_bf16_f32 v136, v138, v139
	v_cvt_pk_bf16_f32 v137, v140, v141
	v_cvt_pk_bf16_f32 v142, v142, v143
	v_cvt_pk_bf16_f32 v143, v144, v145
	v_cvt_pk_bf16_f32 v144, v146, v147
	v_cvt_pk_bf16_f32 v145, v148, v149
	s_waitcnt lgkmcnt(8)
	v_exp_f32_e32 v76, v76
	v_exp_f32_e32 v77, v77
	v_mfma_f32_16x16x32_bf16 v[54:57], v[178:181], v[134:137], v[54:57]
	v_exp_f32_e32 v78, v78
	v_exp_f32_e32 v79, v79
	v_mfma_f32_16x16x32_bf16 v[58:61], v[182:185], v[134:137], v[58:61]
	v_exp_f32_e32 v80, v80
	v_exp_f32_e32 v81, v81
	v_mfma_f32_16x16x32_bf16 v[62:65], v[186:189], v[134:137], v[62:65]
	v_exp_f32_e32 v82, v82
	v_exp_f32_e32 v83, v83
	v_mfma_f32_16x16x32_bf16 v[66:69], v[190:193], v[134:137], v[66:69]
	v_exp_f32_e32 v84, v84
	v_exp_f32_e32 v85, v85
	s_waitcnt lgkmcnt(0)
	v_mfma_f32_16x16x32_bf16 v[54:57], v[194:197], v[142:145], v[54:57]
	v_exp_f32_e32 v86, v86
	v_exp_f32_e32 v87, v87
	v_mfma_f32_16x16x32_bf16 v[58:61], v[198:201], v[142:145], v[58:61]
	v_exp_f32_e32 v88, v88
	v_exp_f32_e32 v89, v89
	v_mfma_f32_16x16x32_bf16 v[62:65], v[202:205], v[142:145], v[62:65]
	v_exp_f32_e32 v90, v90
	v_exp_f32_e32 v91, v91
	v_mfma_f32_16x16x32_bf16 v[66:69], v[206:209], v[142:145], v[66:69]
	v_add_f32_e32 v155, v76, v77
	v_add_f32_e32 v159, v78, v79
	v_add_f32_e32 v155, v155, v80
	v_add_f32_e32 v159, v159, v81
	v_add_f32_e32 v155, v155, v82
	v_add_f32_e32 v159, v159, v83
	v_add_f32_e32 v155, v155, v84
	v_add_f32_e32 v159, v159, v85
	v_add_f32_e32 v155, v155, v86
	v_add_f32_e32 v159, v159, v87
	v_add_f32_e32 v155, v155, v88
	v_add_f32_e32 v159, v159, v89
	v_add_f32_e32 v155, v155, v90
	v_add_f32_e32 v159, v159, v91
	v_add_f32_e32 v155, v155, v159
	v_add_f32_e32 v124, v124, v155
	v_cvt_pk_bf16_f32 v76, v76, v77
	v_cvt_pk_bf16_f32 v77, v78, v79
	v_cvt_pk_bf16_f32 v78, v80, v81
	v_cvt_pk_bf16_f32 v79, v82, v83
	v_cvt_pk_bf16_f32 v84, v84, v85
	v_cvt_pk_bf16_f32 v85, v86, v87
	v_mfma_f32_16x16x32_bf16 v[4:7], v[178:181], v[76:79], v[4:7]
	v_cvt_pk_bf16_f32 v86, v88, v89
	v_mfma_f32_16x16x32_bf16 v[10:13], v[182:185], v[76:79], v[10:13]
	v_cvt_pk_bf16_f32 v87, v90, v91
	v_mfma_f32_16x16x32_bf16 v[14:17], v[186:189], v[76:79], v[14:17]
	v_mfma_f32_16x16x32_bf16 v[18:21], v[190:193], v[76:79], v[18:21]
	v_mfma_f32_16x16x32_bf16 v[4:7], v[194:197], v[84:87], v[4:7]
	v_mfma_f32_16x16x32_bf16 v[10:13], v[198:201], v[84:87], v[10:13]
	v_mfma_f32_16x16x32_bf16 v[14:17], v[202:205], v[84:87], v[14:17]
	v_mfma_f32_16x16x32_bf16 v[18:21], v[206:209], v[84:87], v[18:21]
	s_branch .Lat_end_1
.Lat_resc0_1:
	ds_bpermute_b32 v158, v168, v156
	s_waitcnt lgkmcnt(0)
	v_max_f32_e32 v156, v156, v158
	ds_bpermute_b32 v158, v169, v156
	s_waitcnt lgkmcnt(0)
	v_max_f32_e32 v156, v156, v158
	v_max_f32_e32 v160, 0, v156
	v_exp_f32_e64 v150, -v160
	v_cndmask_b32_e64 v160, v160, v156, s[14:15]
	v_mul_f32_e32 v54, v54, v150
	v_mul_f32_e32 v55, v55, v150
	v_mul_f32_e32 v56, v56, v150
	v_mul_f32_e32 v57, v57, v150
	v_mul_f32_e32 v58, v58, v150
	v_mul_f32_e32 v59, v59, v150
	v_mul_f32_e32 v60, v60, v150
	v_mul_f32_e32 v61, v61, v150
	v_mul_f32_e32 v62, v62, v150
	v_mul_f32_e32 v63, v63, v150
	v_mul_f32_e32 v64, v64, v150
	v_mul_f32_e32 v65, v65, v150
	v_mul_f32_e32 v66, v66, v150
	v_mul_f32_e32 v67, v67, v150
	v_mul_f32_e32 v68, v68, v150
	v_mul_f32_e32 v69, v69, v150
	v_mul_f32_e32 v125, v125, v150
	v_sub_f32_e32 v134, v134, v160
	v_sub_f32_e32 v135, v135, v160
	v_sub_f32_e32 v136, v136, v160
	v_sub_f32_e32 v137, v137, v160
	v_sub_f32_e32 v138, v138, v160
	v_sub_f32_e32 v139, v139, v160
	v_sub_f32_e32 v140, v140, v160
	v_sub_f32_e32 v141, v141, v160
	v_sub_f32_e32 v142, v142, v160
	v_sub_f32_e32 v143, v143, v160
	v_sub_f32_e32 v144, v144, v160
	v_sub_f32_e32 v145, v145, v160
	v_sub_f32_e32 v146, v146, v160
	v_sub_f32_e32 v147, v147, v160
	v_sub_f32_e32 v148, v148, v160
	v_sub_f32_e32 v149, v149, v160
	v_sub_f32_e32 v226, v226, v160
	v_sub_f32_e32 v227, v227, v160
	v_sub_f32_e32 v228, v228, v160
	v_sub_f32_e32 v229, v229, v160
	s_branch .Lat_cont0_1
.Lat_resc1_1:
	ds_bpermute_b32 v159, v168, v157
	s_waitcnt lgkmcnt(0)
	v_max_f32_e32 v157, v157, v159
	ds_bpermute_b32 v159, v169, v157
	s_waitcnt lgkmcnt(0)
	v_max_f32_e32 v157, v157, v159
	v_max_f32_e32 v161, 0, v157
	v_exp_f32_e64 v152, -v161
	v_cndmask_b32_e64 v161, v161, v157, s[14:15]
	v_mul_f32_e32 v4, v4, v152
	v_mul_f32_e32 v5, v5, v152
	v_mul_f32_e32 v6, v6, v152
	v_mul_f32_e32 v7, v7, v152
	v_mul_f32_e32 v10, v10, v152
	v_mul_f32_e32 v11, v11, v152
	v_mul_f32_e32 v12, v12, v152
	v_mul_f32_e32 v13, v13, v152
	v_mul_f32_e32 v14, v14, v152
	v_mul_f32_e32 v15, v15, v152
	v_mul_f32_e32 v16, v16, v152
	v_mul_f32_e32 v17, v17, v152
	v_mul_f32_e32 v18, v18, v152
	v_mul_f32_e32 v19, v19, v152
	v_mul_f32_e32 v20, v20, v152
	v_mul_f32_e32 v21, v21, v152
	v_mul_f32_e32 v124, v124, v152
	v_sub_f32_e32 v76, v76, v161
	v_sub_f32_e32 v77, v77, v161
	v_sub_f32_e32 v78, v78, v161
	v_sub_f32_e32 v79, v79, v161
	v_sub_f32_e32 v80, v80, v161
	v_sub_f32_e32 v81, v81, v161
	v_sub_f32_e32 v82, v82, v161
	v_sub_f32_e32 v83, v83, v161
	v_sub_f32_e32 v84, v84, v161
	v_sub_f32_e32 v85, v85, v161
	v_sub_f32_e32 v86, v86, v161
	v_sub_f32_e32 v87, v87, v161
	v_sub_f32_e32 v88, v88, v161
	v_sub_f32_e32 v89, v89, v161
	v_sub_f32_e32 v90, v90, v161
	v_sub_f32_e32 v91, v91, v161
	v_sub_f32_e32 v230, v230, v161
	v_sub_f32_e32 v231, v231, v161
	v_sub_f32_e32 v232, v232, v161
	v_sub_f32_e32 v233, v233, v161
	s_branch .Lat_cont1_1
.Lat_end_1:
.LBB0_521:
	s_or_b64 exec, exec, s[8:9]
	s_bitcmp1_b32 s40, 0
	s_cselect_b32 s8, 0x5800, 0
	s_add_i32 s12, s8, 0
	v_add_u32_e32 v8, s12, v164
	s_waitcnt vmcnt(1)
	ds_write_b128 v8, v[46:49]
	s_and_saveexec_b64 s[8:9], s[4:5]
	s_cbranch_execz .LBB0_523
	v_add_u32_e32 v8, s12, v165
	s_waitcnt vmcnt(0)
	ds_write_b128 v8, v[50:53]
	v_mov_b64_e32 v[52:53], v[2:3]
	v_mov_b64_e32 v[50:51], v[0:1]

; #define PG8_LAS __attribute__((address_space(3)))
; __device__ void phase_attn(KP p, PG8_LAS unsigned char* lds, float* ldsf, int tid_in) {
;     ...
;             for (int kt = 0; kt < nt; ++kt) {
;                 if (kt + 1 < nt) AT_GLOAD(kt + 1);
;                 if (kt <= cw) {
;                     const PG8_LAS unsigned char* kb = lds + (kt & 1) * BUF;
;                     f32x4 st[4][2];
; #pragma unroll
;                     for (int f = 0; f < 4; ++f) {
;                         const bf16x8 a0 = *(const PG8_LAS bf16x8*)(kb + ka_rd + f * 16 * KS * 2);
;                         const bf16x8 a1 = *(const PG8_LAS bf16x8*)(kb + ka_rd + f * 16 * KS * 2 + 64);
;                         const bf16x8 a2 = *(const PG8_LAS bf16x8*)(kb + ka_rd + f * 16 * KS * 2 + 128);
; #pragma unroll
;                         for (int nb = 0; nb < 2; ++nb) {
;                             f32x4 c = {0.f, 0.f, 0.f, 0.f};
;                             c = __builtin_amdgcn_mfma_f32_16x16x32_bf16(a0, qf[0][nb], c, 0, 0, 0);
;                             c = __builtin_amdgcn_mfma_f32_16x16x32_bf16(a1, qf[1][nb], c, 0, 0, 0);
;                             c = __builtin_amdgcn_mfma_f32_16x16x32_bf16(a2, qf[2][nb], c, 0, 0, 0);
;                             st[f][nb] = c;
;                         }
;                     }
; #pragma unroll
;                     for (int nb = 0; nb < 2; ++nb) {
;                         float mx = -1e30f;
; #pragma unroll
;                         for (int f = 0; f < 4; ++f)
; #pragma unroll
;                             for (int r = 0; r < 4; ++r) mx = fmaxf(mx, st[f][nb][r]);
;                         mx = fmaxf(mx, shx(mx, 16, lane)); mx = fmaxf(mx, shx(mx, 32, lane));
;                         const float mn = fmaxf(mrun[nb], mx), al = __builtin_amdgcn_exp2f(mrun[nb] - mn); mrun[nb] = mn;
;                         float ps = 0.f;
; #pragma unroll
;                         for (int f = 0; f < 4; ++f)
; #pragma unroll
;                             for (int r = 0; r < 4; ++r) { const float e = __builtin_amdgcn_exp2f(st[f][nb][r] - mn); st[f][nb][r] = e; ps += e; }
;                         lrun[nb] = lrun[nb] * al + ps;
; #pragma unroll
;                         for (int df = 0; df < 4; ++df) o[df][nb] *= al;
;                     }
.LBB0_525:
	s_add_i32 s8, s0, -2
	v_cmp_lt_i32_e32 vcc, s8, v171
	s_and_saveexec_b64 s[8:9], vcc
	s_cbranch_execz .LBB0_511
	v_add_u32_e32 v8, s12, v167
	ds_read_b128 v[178:181], v8
	ds_read_b128 v[182:185], v8 offset:64
	ds_read_b128 v[186:189], v8 offset:128
	ds_read_b128 v[190:193], v8 offset:3328
	ds_read_b128 v[194:197], v8 offset:3392
	ds_read_b128 v[198:201], v8 offset:3456
	ds_read_b128 v[202:205], v8 offset:6656
	ds_read_b128 v[206:209], v8 offset:6720
	ds_read_b128 v[210:213], v8 offset:6784
	ds_read_b128 v[214:217], v8 offset:9984
	ds_read_b128 v[218:221], v8 offset:10048
	ds_read_b128 v[222:225], v8 offset:10112
	v_add_u32_e32 v92, s12, v170
	s_mov_b64 s[14:15], 0
	s_waitcnt lgkmcnt(9)
	v_mfma_f32_16x16x32_bf16 v[134:137], v[178:181], v[22:25], v[226:229]
	v_mfma_f32_16x16x32_bf16 v[134:137], v[182:185], v[26:29], v[134:137]
	v_mfma_f32_16x16x32_bf16 v[134:137], v[186:189], v[38:41], v[134:137]
	s_waitcnt lgkmcnt(6)
	v_mfma_f32_16x16x32_bf16 v[138:141], v[190:193], v[22:25], v[226:229]
	v_mfma_f32_16x16x32_bf16 v[138:141], v[194:197], v[26:29], v[138:141]
	v_mfma_f32_16x16x32_bf16 v[138:141], v[198:201], v[38:41], v[138:141]
	s_waitcnt lgkmcnt(3)
	v_mfma_f32_16x16x32_bf16 v[142:145], v[202:205], v[22:25], v[226:229]
	v_mfma_f32_16x16x32_bf16 v[142:145], v[206:209], v[26:29], v[142:145]
	v_mfma_f32_16x16x32_bf16 v[142:145], v[210:213], v[38:41], v[142:145]
	s_waitcnt lgkmcnt(0)
	v_mfma_f32_16x16x32_bf16 v[146:149], v[214:217], v[22:25], v[226:229]
	v_mfma_f32_16x16x32_bf16 v[146:149], v[218:221], v[26:29], v[146:149]
	v_mfma_f32_16x16x32_bf16 v[146:149], v[222:225], v[38:41], v[146:149]
	v_mfma_f32_16x16x32_bf16 v[76:79], v[178:181], v[42:45], v[230:233]
	v_max3_f32 v156, v134, v135, v136
	v_max3_f32 v156, v156, v137, v138
	v_mfma_f32_16x16x32_bf16 v[76:79], v[182:185], v[30:33], v[76:79]
	v_max3_f32 v156, v156, v139, v140
	v_max3_f32 v156, v156, v141, v142
	v_mfma_f32_16x16x32_bf16 v[76:79], v[186:189], v[34:37], v[76:79]
	v_max3_f32 v156, v156, v143, v144
	v_max3_f32 v156, v156, v145, v146
	v_mfma_f32_16x16x32_bf16 v[80:83], v[190:193], v[42:45], v[230:233]
	v_max3_f32 v156, v156, v147, v148
	v_max_f32_e32 v156, v156, v149
	v_cmp_lt_f32_e32 vcc, 0x41000000, v156
	v_mfma_f32_16x16x32_bf16 v[80:83], v[194:197], v[30:33], v[80:83]
	v_mfma_f32_16x16x32_bf16 v[80:83], v[198:201], v[34:37], v[80:83]
	s_or_b64 vcc, vcc, s[14:15]
	s_cbranch_vccnz .Lat_resc0_2
